# v17: v15 plus the weight-transpose loops of phase 0 issue all four row loads of a 64x64 tile together (one memory round trip per tile instead of two)
# speedup vs baseline: 1.0057x; 1.0057x over previous
; DI void transpose_job(const float* __restrict__ src, int K, int N, int Npad, bf16_t* __restrict__ dst, int mode, char* smem) {
;     ...
;   for (int tile = blockIdx.x; tile < tn * tk; tile += gridDim.x) {
;     const int n0 = (tile % tn) * 64, k0 = (tile / tn) * 64;
; #pragma unroll
;     for (int i = 0; i < 4; ++i) {
;       const int kr = (tid >> 4) + 16 * i, nc = (tid & 15) * 4, n = n0 + nc;
;       float4 v = make_float4(0.f, 0.f, 0.f, 0.f);
;       if (n < N) { const f32x4 t4 = __builtin_nontemporal_load((const f32x4*)(src + (size_t)(k0 + kr) * N + n)); v = make_float4(t4[0], t4[1], t4[2], t4[3]); }
;       t[kr * 65 + nc + 0] = v.x; t[kr * 65 + nc + 1] = v.y; t[kr * 65 + nc + 2] = v.z; t[kr * 65 + nc + 3] = v.w;
;     }
.LBB0_24:
	s_or_saveexec_b64 s[26:27], s[24:25]
	s_lshl_b32 s24, s34, 6
	v_mov_b32_e32 v4, 0
	v_mov_b32_e32 v5, 0
	v_mov_b32_e32 v6, 0
	v_mov_b32_e32 v7, 0
	v_mov_b32_e32 v0, 0
	v_mov_b32_e32 v1, 0
	v_mov_b32_e32 v2, 0
	v_mov_b32_e32 v3, 0
	s_xor_b64 exec, exec, s[26:27]
	s_cbranch_execz .LBB0_21
	v_ashrrev_i32_e32 v11, 31, v10
	v_lshl_add_u64 v[10:11], v[10:11], 2, s[0:1]
	v_add_u32_e32 v27, s24, v13
	v_mad_i64_i32 v[0:1], s[34:35], v27, s37, v[10:11]
	global_load_dwordx4 v[0:3], v[0:1], off nt
	v_add_u32_e32 v4, 16, v27
	v_mad_i64_i32 v[4:5], s[34:35], v4, s37, v[10:11]
	global_load_dwordx4 v[4:7], v[4:5], off nt
	v_add_u32_e32 v64, 32, v27
	v_add_u32_e32 v68, 48, v27
	v_mad_i64_i32 v[64:65], s[34:35], v64, s37, v[10:11]
	v_mad_i64_i32 v[68:69], s[34:35], v68, s37, v[10:11]
	global_load_dwordx4 v[64:67], v[64:65], off nt
	s_nop 0
	global_load_dwordx4 v[68:71], v[68:69], off nt
	s_waitcnt vmcnt(3)
	ds_write2_b32 v17, v0, v1 offset1:1
	ds_write2_b32 v17, v2, v3 offset0:2 offset1:3
	s_waitcnt vmcnt(2)
	ds_write2_b32 v18, v4, v5 offset1:1
	ds_write2_b32 v19, v6, v7 offset1:1
	s_waitcnt vmcnt(0)
	v_mov_b32_e32 v0, v64
	v_mov_b32_e32 v1, v65
	v_mov_b32_e32 v2, v66
	v_mov_b32_e32 v3, v67
	v_mov_b32_e32 v4, v68
	v_mov_b32_e32 v5, v69
	v_mov_b32_e32 v6, v70
	v_mov_b32_e32 v7, v71
	s_branch .LBB0_21

; DI void transpose_job(const float* __restrict__ src, int K, int N, int Npad, bf16_t* __restrict__ dst, int mode, char* smem) {
;     ...
;   for (int tile = blockIdx.x; tile < tn * tk; tile += gridDim.x) {
;     const int n0 = (tile % tn) * 64, k0 = (tile / tn) * 64;
; #pragma unroll
;     for (int i = 0; i < 4; ++i) {
;       const int kr = (tid >> 4) + 16 * i, nc = (tid & 15) * 4, n = n0 + nc;
;       float4 v = make_float4(0.f, 0.f, 0.f, 0.f);
;       if (n < N) { const f32x4 t4 = __builtin_nontemporal_load((const f32x4*)(src + (size_t)(k0 + kr) * N + n)); v = make_float4(t4[0], t4[1], t4[2], t4[3]); }
;       t[kr * 65 + nc + 0] = v.x; t[kr * 65 + nc + 1] = v.y; t[kr * 65 + nc + 2] = v.z; t[kr * 65 + nc + 3] = v.w;
;     }
.LBB0_31:
	s_or_saveexec_b64 s[26:27], s[24:25]
	s_lshl_b32 s24, s34, 6
	v_mov_b32_e32 v4, 0
	v_mov_b32_e32 v5, 0
	v_mov_b32_e32 v6, 0
	v_mov_b32_e32 v7, 0
	v_mov_b32_e32 v0, 0
	v_mov_b32_e32 v1, 0
	v_mov_b32_e32 v2, 0
	v_mov_b32_e32 v3, 0
	s_xor_b64 exec, exec, s[26:27]
	s_cbranch_execz .LBB0_28
	v_ashrrev_i32_e32 v11, 31, v10
	v_lshl_add_u64 v[10:11], v[10:11], 2, s[0:1]
	v_add_u32_e32 v27, s24, v13
	v_mad_i64_i32 v[0:1], s[34:35], v27, s38, v[10:11]
	global_load_dwordx4 v[0:3], v[0:1], off nt
	v_add_u32_e32 v4, 16, v27
	v_mad_i64_i32 v[4:5], s[34:35], v4, s38, v[10:11]
	global_load_dwordx4 v[4:7], v[4:5], off nt
	v_add_u32_e32 v64, 32, v27
	v_add_u32_e32 v68, 48, v27
	v_mad_i64_i32 v[64:65], s[34:35], v64, s38, v[10:11]
	v_mad_i64_i32 v[68:69], s[34:35], v68, s38, v[10:11]
	global_load_dwordx4 v[64:67], v[64:65], off nt
	s_nop 0
	global_load_dwordx4 v[68:71], v[68:69], off nt
	s_waitcnt vmcnt(3)
	ds_write2_b32 v17, v0, v1 offset1:1
	ds_write2_b32 v17, v2, v3 offset0:2 offset1:3
	s_waitcnt vmcnt(2)
	ds_write2_b32 v18, v4, v5 offset1:1
	ds_write2_b32 v19, v6, v7 offset1:1
	s_waitcnt vmcnt(0)
	v_mov_b32_e32 v0, v64
	v_mov_b32_e32 v1, v65
	v_mov_b32_e32 v2, v66
	v_mov_b32_e32 v3, v67
	v_mov_b32_e32 v4, v68
	v_mov_b32_e32 v5, v69
	v_mov_b32_e32 v6, v70
	v_mov_b32_e32 v7, v71
	s_branch .LBB0_28

; DI void transpose_job(const float* __restrict__ src, int K, int N, int Npad, bf16_t* __restrict__ dst, int mode, char* smem) {
;     ...
;   for (int tile = blockIdx.x; tile < tn * tk; tile += gridDim.x) {
;     const int n0 = (tile % tn) * 64, k0 = (tile / tn) * 64;
; #pragma unroll
;     for (int i = 0; i < 4; ++i) {
;       const int kr = (tid >> 4) + 16 * i, nc = (tid & 15) * 4, n = n0 + nc;
;       float4 v = make_float4(0.f, 0.f, 0.f, 0.f);
;       if (n < N) { const f32x4 t4 = __builtin_nontemporal_load((const f32x4*)(src + (size_t)(k0 + kr) * N + n)); v = make_float4(t4[0], t4[1], t4[2], t4[3]); }
;       t[kr * 65 + nc + 0] = v.x; t[kr * 65 + nc + 1] = v.y; t[kr * 65 + nc + 2] = v.z; t[kr * 65 + nc + 3] = v.w;
;     }
.LBB0_38:
	s_or_saveexec_b64 s[28:29], s[26:27]
	s_lshl_b32 s26, s42, 6
	v_mov_b32_e32 v4, 0
	v_mov_b32_e32 v5, 0
	v_mov_b32_e32 v6, 0
	v_mov_b32_e32 v7, 0
	v_mov_b32_e32 v0, 0
	v_mov_b32_e32 v1, 0
	v_mov_b32_e32 v2, 0
	v_mov_b32_e32 v3, 0
	s_xor_b64 exec, exec, s[28:29]
	s_cbranch_execz .LBB0_35
	v_add_u32_e32 v28, s26, v13
	v_ashrrev_i32_e32 v11, 31, v10
	v_ashrrev_i32_e32 v29, 31, v28
	v_lshl_add_u64 v[10:11], v[10:11], 2, s[0:1]
	v_lshlrev_b64 v[0:1], 13, v[28:29]
	v_add_u32_e32 v4, 16, v28
	v_lshl_add_u64 v[0:1], v[10:11], 0, v[0:1]
	v_ashrrev_i32_e32 v5, 31, v4
	global_load_dwordx4 v[0:3], v[0:1], off nt
	v_lshlrev_b64 v[4:5], 13, v[4:5]
	v_lshl_add_u64 v[4:5], v[10:11], 0, v[4:5]
	global_load_dwordx4 v[4:7], v[4:5], off nt
	v_add_u32_e32 v64, 32, v28
	v_add_u32_e32 v68, 48, v28
	v_ashrrev_i32_e32 v65, 31, v64
	v_ashrrev_i32_e32 v69, 31, v68
	v_lshlrev_b64 v[64:65], 13, v[64:65]
	v_lshlrev_b64 v[68:69], 13, v[68:69]
	v_lshl_add_u64 v[64:65], v[10:11], 0, v[64:65]
	v_lshl_add_u64 v[68:69], v[10:11], 0, v[68:69]
	global_load_dwordx4 v[64:67], v[64:65], off nt
	s_nop 0
	global_load_dwordx4 v[68:71], v[68:69], off nt
	s_waitcnt vmcnt(3)
	ds_write2_b32 v17, v0, v1 offset1:1
	ds_write2_b32 v17, v2, v3 offset0:2 offset1:3
	s_waitcnt vmcnt(2)
	ds_write2_b32 v18, v4, v5 offset1:1
	ds_write2_b32 v19, v6, v7 offset1:1
	s_waitcnt vmcnt(0)
	v_mov_b32_e32 v0, v64
	v_mov_b32_e32 v1, v65
	v_mov_b32_e32 v2, v66
	v_mov_b32_e32 v3, v67
	v_mov_b32_e32 v4, v68
	v_mov_b32_e32 v5, v69
	v_mov_b32_e32 v6, v70
	v_mov_b32_e32 v7, v71
	s_branch .LBB0_35

; DI void transpose_job(const float* __restrict__ src, int K, int N, int Npad, bf16_t* __restrict__ dst, int mode, char* smem) {
;     ...
;   for (int tile = blockIdx.x; tile < tn * tk; tile += gridDim.x) {
;     const int n0 = (tile % tn) * 64, k0 = (tile / tn) * 64;
; #pragma unroll
;     for (int i = 0; i < 4; ++i) {
;       const int kr = (tid >> 4) + 16 * i, nc = (tid & 15) * 4, n = n0 + nc;
;       float4 v = make_float4(0.f, 0.f, 0.f, 0.f);
;       if (n < N) { const f32x4 t4 = __builtin_nontemporal_load((const f32x4*)(src + (size_t)(k0 + kr) * N + n)); v = make_float4(t4[0], t4[1], t4[2], t4[3]); }
;       t[kr * 65 + nc + 0] = v.x; t[kr * 65 + nc + 1] = v.y; t[kr * 65 + nc + 2] = v.z; t[kr * 65 + nc + 3] = v.w;
;     }
.LBB0_52:
	s_or_saveexec_b64 s[28:29], s[26:27]
	s_lshl_b32 s26, s42, 6
	v_mov_b32_e32 v4, 0
	v_mov_b32_e32 v5, 0
	v_mov_b32_e32 v6, 0
	v_mov_b32_e32 v7, 0
	v_mov_b32_e32 v0, 0
	v_mov_b32_e32 v1, 0
	v_mov_b32_e32 v2, 0
	v_mov_b32_e32 v3, 0
	s_xor_b64 exec, exec, s[28:29]
	s_cbranch_execz .LBB0_49
	v_ashrrev_i32_e32 v11, 31, v10
	v_lshl_add_u64 v[10:11], v[10:11], 2, s[0:1]
	v_add_u32_e32 v20, s26, v13
	v_mad_i64_i32 v[0:1], s[42:43], v20, s40, v[10:11]
	global_load_dwordx4 v[0:3], v[0:1], off nt
	v_add_u32_e32 v4, 16, v20
	v_mad_i64_i32 v[4:5], s[42:43], v4, s40, v[10:11]
	global_load_dwordx4 v[4:7], v[4:5], off nt
	v_add_u32_e32 v64, 32, v20
	v_add_u32_e32 v68, 48, v20
	v_mad_i64_i32 v[64:65], s[42:43], v64, s40, v[10:11]
	v_mad_i64_i32 v[68:69], s[42:43], v68, s40, v[10:11]
	global_load_dwordx4 v[64:67], v[64:65], off nt
	s_nop 0
	global_load_dwordx4 v[68:71], v[68:69], off nt
	s_waitcnt vmcnt(3)
	ds_write2_b32 v17, v0, v1 offset1:1
	ds_write2_b32 v17, v2, v3 offset0:2 offset1:3
	s_waitcnt vmcnt(2)
	ds_write2_b32 v18, v4, v5 offset1:1
	ds_write2_b32 v19, v6, v7 offset1:1
	s_waitcnt vmcnt(0)
	v_mov_b32_e32 v0, v64
	v_mov_b32_e32 v1, v65
	v_mov_b32_e32 v2, v66
	v_mov_b32_e32 v3, v67
	v_mov_b32_e32 v4, v68
	v_mov_b32_e32 v5, v69
	v_mov_b32_e32 v6, v70
	v_mov_b32_e32 v7, v71
	s_branch .LBB0_49

; DI void transpose_job(const float* __restrict__ src, int K, int N, int Npad, bf16_t* __restrict__ dst, int mode, char* smem) {
;     ...
;   for (int tile = blockIdx.x; tile < tn * tk; tile += gridDim.x) {
;     const int n0 = (tile % tn) * 64, k0 = (tile / tn) * 64;
; #pragma unroll
;     for (int i = 0; i < 4; ++i) {
;       const int kr = (tid >> 4) + 16 * i, nc = (tid & 15) * 4, n = n0 + nc;
;       float4 v = make_float4(0.f, 0.f, 0.f, 0.f);
;       if (n < N) { const f32x4 t4 = __builtin_nontemporal_load((const f32x4*)(src + (size_t)(k0 + kr) * N + n)); v = make_float4(t4[0], t4[1], t4[2], t4[3]); }
;       t[kr * 65 + nc + 0] = v.x; t[kr * 65 + nc + 1] = v.y; t[kr * 65 + nc + 2] = v.z; t[kr * 65 + nc + 3] = v.w;
;     }
.LBB0_59:
	s_or_saveexec_b64 s[28:29], s[26:27]
	s_lshl_b32 s26, s42, 6
	v_mov_b32_e32 v4, 0
	v_mov_b32_e32 v5, 0
	v_mov_b32_e32 v6, 0
	v_mov_b32_e32 v7, 0
	v_mov_b32_e32 v0, 0
	v_mov_b32_e32 v1, 0
	v_mov_b32_e32 v2, 0
	v_mov_b32_e32 v3, 0
	s_xor_b64 exec, exec, s[28:29]
	s_cbranch_execz .LBB0_56
	v_add_u32_e32 v20, s26, v13
	v_ashrrev_i32_e32 v11, 31, v10
	v_ashrrev_i32_e32 v21, 31, v20
	v_lshl_add_u64 v[10:11], v[10:11], 2, s[0:1]
	v_lshlrev_b64 v[0:1], 9, v[20:21]
	v_add_u32_e32 v4, 16, v20
	v_lshl_add_u64 v[0:1], v[10:11], 0, v[0:1]
	v_ashrrev_i32_e32 v5, 31, v4
	global_load_dwordx4 v[0:3], v[0:1], off nt
	v_lshlrev_b64 v[4:5], 9, v[4:5]
	v_lshl_add_u64 v[4:5], v[10:11], 0, v[4:5]
	global_load_dwordx4 v[4:7], v[4:5], off nt
	v_add_u32_e32 v64, 32, v20
	v_add_u32_e32 v68, 48, v20
	v_ashrrev_i32_e32 v65, 31, v64
	v_ashrrev_i32_e32 v69, 31, v68
	v_lshlrev_b64 v[64:65], 9, v[64:65]
	v_lshlrev_b64 v[68:69], 9, v[68:69]
	v_lshl_add_u64 v[64:65], v[10:11], 0, v[64:65]
	v_lshl_add_u64 v[68:69], v[10:11], 0, v[68:69]
	global_load_dwordx4 v[64:67], v[64:65], off nt
	s_nop 0
	global_load_dwordx4 v[68:71], v[68:69], off nt
	s_waitcnt vmcnt(3)
	ds_write2_b32 v17, v0, v1 offset1:1
	ds_write2_b32 v17, v2, v3 offset0:2 offset1:3
	s_waitcnt vmcnt(2)
	ds_write2_b32 v18, v4, v5 offset1:1
	ds_write2_b32 v19, v6, v7 offset1:1
	s_waitcnt vmcnt(0)
	v_mov_b32_e32 v0, v64
	v_mov_b32_e32 v1, v65
	v_mov_b32_e32 v2, v66
	v_mov_b32_e32 v3, v67
	v_mov_b32_e32 v4, v68
	v_mov_b32_e32 v5, v69
	v_mov_b32_e32 v6, v70
	v_mov_b32_e32 v7, v71
	s_branch .LBB0_56

; DI void transpose_job(const float* __restrict__ src, int K, int N, int Npad, bf16_t* __restrict__ dst, int mode, char* smem) {
;     ...
;   for (int tile = blockIdx.x; tile < tn * tk; tile += gridDim.x) {
;     const int n0 = (tile % tn) * 64, k0 = (tile / tn) * 64;
; #pragma unroll
;     for (int i = 0; i < 4; ++i) {
;       const int kr = (tid >> 4) + 16 * i, nc = (tid & 15) * 4, n = n0 + nc;
;       float4 v = make_float4(0.f, 0.f, 0.f, 0.f);
;       if (n < N) { const f32x4 t4 = __builtin_nontemporal_load((const f32x4*)(src + (size_t)(k0 + kr) * N + n)); v = make_float4(t4[0], t4[1], t4[2], t4[3]); }
;       t[kr * 65 + nc + 0] = v.x; t[kr * 65 + nc + 1] = v.y; t[kr * 65 + nc + 2] = v.z; t[kr * 65 + nc + 3] = v.w;
;     }
.LBB0_66:
	s_or_saveexec_b64 s[30:31], s[28:29]
	s_lshl_b32 s28, s44, 6
	v_mov_b32_e32 v4, 0
	v_mov_b32_e32 v5, 0
	v_mov_b32_e32 v6, 0
	v_mov_b32_e32 v7, 0
	v_mov_b32_e32 v0, 0
	v_mov_b32_e32 v1, 0
	v_mov_b32_e32 v2, 0
	v_mov_b32_e32 v3, 0
	s_xor_b64 exec, exec, s[30:31]
	s_cbranch_execz .LBB0_63
	v_add_u32_e32 v20, s28, v13
	v_ashrrev_i32_e32 v11, 31, v10
	v_ashrrev_i32_e32 v21, 31, v20
	v_lshl_add_u64 v[10:11], v[10:11], 2, s[8:9]
	v_lshlrev_b64 v[0:1], 9, v[20:21]
	v_add_u32_e32 v4, 16, v20
	v_lshl_add_u64 v[0:1], v[10:11], 0, v[0:1]
	v_ashrrev_i32_e32 v5, 31, v4
	global_load_dwordx4 v[0:3], v[0:1], off nt
	v_lshlrev_b64 v[4:5], 9, v[4:5]
	v_lshl_add_u64 v[4:5], v[10:11], 0, v[4:5]
	global_load_dwordx4 v[4:7], v[4:5], off nt
	v_add_u32_e32 v64, 32, v20
	v_add_u32_e32 v68, 48, v20
	v_ashrrev_i32_e32 v65, 31, v64
	v_ashrrev_i32_e32 v69, 31, v68
	v_lshlrev_b64 v[64:65], 9, v[64:65]
	v_lshlrev_b64 v[68:69], 9, v[68:69]
	v_lshl_add_u64 v[64:65], v[10:11], 0, v[64:65]
	v_lshl_add_u64 v[68:69], v[10:11], 0, v[68:69]
	global_load_dwordx4 v[64:67], v[64:65], off nt
	s_nop 0
	global_load_dwordx4 v[68:71], v[68:69], off nt
	s_waitcnt vmcnt(3)
	ds_write2_b32 v17, v0, v1 offset1:1
	ds_write2_b32 v17, v2, v3 offset0:2 offset1:3
	s_waitcnt vmcnt(2)
	ds_write2_b32 v18, v4, v5 offset1:1
	ds_write2_b32 v19, v6, v7 offset1:1
	s_waitcnt vmcnt(0)
	v_mov_b32_e32 v0, v64
	v_mov_b32_e32 v1, v65
	v_mov_b32_e32 v2, v66
	v_mov_b32_e32 v3, v67
	v_mov_b32_e32 v4, v68
	v_mov_b32_e32 v5, v69
	v_mov_b32_e32 v6, v70
	v_mov_b32_e32 v7, v71
	s_branch .LBB0_63

; DI void transpose_job(const float* __restrict__ src, int K, int N, int Npad, bf16_t* __restrict__ dst, int mode, char* smem) {
;     ...
;   for (int tile = blockIdx.x; tile < tn * tk; tile += gridDim.x) {
;     const int n0 = (tile % tn) * 64, k0 = (tile / tn) * 64;
; #pragma unroll
;     for (int i = 0; i < 4; ++i) {
;       const int kr = (tid >> 4) + 16 * i, nc = (tid & 15) * 4, n = n0 + nc;
;       float4 v = make_float4(0.f, 0.f, 0.f, 0.f);
;       if (n < N) { const f32x4 t4 = __builtin_nontemporal_load((const f32x4*)(src + (size_t)(k0 + kr) * N + n)); v = make_float4(t4[0], t4[1], t4[2], t4[3]); }
;       t[kr * 65 + nc + 0] = v.x; t[kr * 65 + nc + 1] = v.y; t[kr * 65 + nc + 2] = v.z; t[kr * 65 + nc + 3] = v.w;
;     }
.LBB0_73:
	s_or_saveexec_b64 s[34:35], s[30:31]
	s_lshl_b32 s30, s47, 6
	v_mov_b32_e32 v4, 0
	v_mov_b32_e32 v5, 0
	v_mov_b32_e32 v6, 0
	v_mov_b32_e32 v7, 0
	v_mov_b32_e32 v0, 0
	v_mov_b32_e32 v1, 0
	v_mov_b32_e32 v2, 0
	v_mov_b32_e32 v3, 0
	s_xor_b64 exec, exec, s[34:35]
	s_cbranch_execz .LBB0_70
	v_add_u32_e32 v20, s30, v13
	v_ashrrev_i32_e32 v11, 31, v10
	v_ashrrev_i32_e32 v21, 31, v20
	v_lshl_add_u64 v[10:11], v[10:11], 2, s[26:27]
	v_lshlrev_b64 v[0:1], 9, v[20:21]
	v_add_u32_e32 v4, 16, v20
	v_lshl_add_u64 v[0:1], v[10:11], 0, v[0:1]
	v_ashrrev_i32_e32 v5, 31, v4
	global_load_dwordx4 v[0:3], v[0:1], off nt
	v_lshlrev_b64 v[4:5], 9, v[4:5]
	v_lshl_add_u64 v[4:5], v[10:11], 0, v[4:5]
	global_load_dwordx4 v[4:7], v[4:5], off nt
	v_add_u32_e32 v64, 32, v20
	v_add_u32_e32 v68, 48, v20
	v_ashrrev_i32_e32 v65, 31, v64
	v_ashrrev_i32_e32 v69, 31, v68
	v_lshlrev_b64 v[64:65], 9, v[64:65]
	v_lshlrev_b64 v[68:69], 9, v[68:69]
	v_lshl_add_u64 v[64:65], v[10:11], 0, v[64:65]
	v_lshl_add_u64 v[68:69], v[10:11], 0, v[68:69]
	global_load_dwordx4 v[64:67], v[64:65], off nt
	s_nop 0
	global_load_dwordx4 v[68:71], v[68:69], off nt
	s_waitcnt vmcnt(3)
	ds_write2_b32 v17, v0, v1 offset1:1
	ds_write2_b32 v17, v2, v3 offset0:2 offset1:3
	s_waitcnt vmcnt(2)
	ds_write2_b32 v18, v4, v5 offset1:1
	ds_write2_b32 v19, v6, v7 offset1:1
	s_waitcnt vmcnt(0)
	v_mov_b32_e32 v0, v64
	v_mov_b32_e32 v1, v65
	v_mov_b32_e32 v2, v66
	v_mov_b32_e32 v3, v67
	v_mov_b32_e32 v4, v68
	v_mov_b32_e32 v5, v69
	v_mov_b32_e32 v6, v70
	v_mov_b32_e32 v7, v71
	s_branch .LBB0_70

; DI void transpose_job(const float* __restrict__ src, int K, int N, int Npad, bf16_t* __restrict__ dst, int mode, char* smem) {
;     ...
;   for (int tile = blockIdx.x; tile < tn * tk; tile += gridDim.x) {
;     const int n0 = (tile % tn) * 64, k0 = (tile / tn) * 64;
; #pragma unroll
;     for (int i = 0; i < 4; ++i) {
;       const int kr = (tid >> 4) + 16 * i, nc = (tid & 15) * 4, n = n0 + nc;
;       float4 v = make_float4(0.f, 0.f, 0.f, 0.f);
;       if (n < N) { const f32x4 t4 = __builtin_nontemporal_load((const f32x4*)(src + (size_t)(k0 + kr) * N + n)); v = make_float4(t4[0], t4[1], t4[2], t4[3]); }
;       t[kr * 65 + nc + 0] = v.x; t[kr * 65 + nc + 1] = v.y; t[kr * 65 + nc + 2] = v.z; t[kr * 65 + nc + 3] = v.w;
;     }
.LBB0_80:
	s_or_saveexec_b64 s[30:31], s[28:29]
	s_lshl_b32 s28, s43, 6
	v_mov_b32_e32 v4, 0
	v_mov_b32_e32 v5, 0
	v_mov_b32_e32 v6, 0
	v_mov_b32_e32 v7, 0
	v_mov_b32_e32 v0, 0
	v_mov_b32_e32 v1, 0
	v_mov_b32_e32 v2, 0
	v_mov_b32_e32 v3, 0
	s_xor_b64 exec, exec, s[30:31]
	s_cbranch_execz .LBB0_77
	v_add_u32_e32 v20, s28, v13
	v_ashrrev_i32_e32 v11, 31, v10
	v_ashrrev_i32_e32 v21, 31, v20
	v_lshl_add_u64 v[10:11], v[10:11], 2, s[0:1]
	v_lshlrev_b64 v[0:1], 9, v[20:21]
	v_add_u32_e32 v4, 16, v20
	v_lshl_add_u64 v[0:1], v[10:11], 0, v[0:1]
	v_ashrrev_i32_e32 v5, 31, v4
	global_load_dwordx4 v[0:3], v[0:1], off nt
	v_lshlrev_b64 v[4:5], 9, v[4:5]
	v_lshl_add_u64 v[4:5], v[10:11], 0, v[4:5]
	global_load_dwordx4 v[4:7], v[4:5], off nt
	v_add_u32_e32 v64, 32, v20
	v_add_u32_e32 v68, 48, v20
	v_ashrrev_i32_e32 v65, 31, v64
	v_ashrrev_i32_e32 v69, 31, v68
	v_lshlrev_b64 v[64:65], 9, v[64:65]
	v_lshlrev_b64 v[68:69], 9, v[68:69]
	v_lshl_add_u64 v[64:65], v[10:11], 0, v[64:65]
	v_lshl_add_u64 v[68:69], v[10:11], 0, v[68:69]
	global_load_dwordx4 v[64:67], v[64:65], off nt
	s_nop 0
	global_load_dwordx4 v[68:71], v[68:69], off nt
	s_waitcnt vmcnt(3)
	ds_write2_b32 v17, v0, v1 offset1:1
	ds_write2_b32 v17, v2, v3 offset0:2 offset1:3
	s_waitcnt vmcnt(2)
	ds_write2_b32 v18, v4, v5 offset1:1
	ds_write2_b32 v19, v6, v7 offset1:1
	s_waitcnt vmcnt(0)
	v_mov_b32_e32 v0, v64
	v_mov_b32_e32 v1, v65
	v_mov_b32_e32 v2, v66
	v_mov_b32_e32 v3, v67
	v_mov_b32_e32 v4, v68
	v_mov_b32_e32 v5, v69
	v_mov_b32_e32 v6, v70
	v_mov_b32_e32 v7, v71
	s_branch .LBB0_77

; DI void transpose_job(const float* __restrict__ src, int K, int N, int Npad, bf16_t* __restrict__ dst, int mode, char* smem) {
;     ...
;   for (int tile = blockIdx.x; tile < tn * tk; tile += gridDim.x) {
;     const int n0 = (tile % tn) * 64, k0 = (tile / tn) * 64;
; #pragma unroll
;     for (int i = 0; i < 4; ++i) {
;       const int kr = (tid >> 4) + 16 * i, nc = (tid & 15) * 4, n = n0 + nc;
;       float4 v = make_float4(0.f, 0.f, 0.f, 0.f);
;       if (n < N) { const f32x4 t4 = __builtin_nontemporal_load((const f32x4*)(src + (size_t)(k0 + kr) * N + n)); v = make_float4(t4[0], t4[1], t4[2], t4[3]); }
;       t[kr * 65 + nc + 0] = v.x; t[kr * 65 + nc + 1] = v.y; t[kr * 65 + nc + 2] = v.z; t[kr * 65 + nc + 3] = v.w;
;     }
.LBB0_87:
	s_or_saveexec_b64 s[28:29], s[26:27]
	s_lshl_b32 s26, s35, 6
	v_mov_b32_e32 v4, 0
	v_mov_b32_e32 v5, 0
	v_mov_b32_e32 v6, 0
	v_mov_b32_e32 v7, 0
	v_mov_b32_e32 v0, 0
	v_mov_b32_e32 v1, 0
	v_mov_b32_e32 v2, 0
	v_mov_b32_e32 v3, 0
	s_xor_b64 exec, exec, s[28:29]
	s_cbranch_execz .LBB0_84
	v_add_u32_e32 v20, s26, v13
	v_ashrrev_i32_e32 v11, 31, v10
	v_ashrrev_i32_e32 v21, 31, v20
	v_lshl_add_u64 v[10:11], v[10:11], 2, s[0:1]
	v_lshlrev_b64 v[0:1], 13, v[20:21]
	v_add_u32_e32 v4, 16, v20
	v_lshl_add_u64 v[0:1], v[10:11], 0, v[0:1]
	v_ashrrev_i32_e32 v5, 31, v4
	global_load_dwordx4 v[0:3], v[0:1], off nt
	v_lshlrev_b64 v[4:5], 13, v[4:5]
	v_lshl_add_u64 v[4:5], v[10:11], 0, v[4:5]
	global_load_dwordx4 v[4:7], v[4:5], off nt
	v_add_u32_e32 v64, 32, v20
	v_add_u32_e32 v68, 48, v20
	v_ashrrev_i32_e32 v65, 31, v64
	v_ashrrev_i32_e32 v69, 31, v68
	v_lshlrev_b64 v[64:65], 13, v[64:65]
	v_lshlrev_b64 v[68:69], 13, v[68:69]
	v_lshl_add_u64 v[64:65], v[10:11], 0, v[64:65]
	v_lshl_add_u64 v[68:69], v[10:11], 0, v[68:69]
	global_load_dwordx4 v[64:67], v[64:65], off nt
	s_nop 0
	global_load_dwordx4 v[68:71], v[68:69], off nt
	s_waitcnt vmcnt(3)
	ds_write2_b32 v17, v0, v1 offset1:1
	ds_write2_b32 v17, v2, v3 offset0:2 offset1:3
	s_waitcnt vmcnt(2)
	ds_write2_b32 v18, v4, v5 offset1:1
	ds_write2_b32 v19, v6, v7 offset1:1
	s_waitcnt vmcnt(0)
	v_mov_b32_e32 v0, v64
	v_mov_b32_e32 v1, v65
	v_mov_b32_e32 v2, v66
	v_mov_b32_e32 v3, v67
	v_mov_b32_e32 v4, v68
	v_mov_b32_e32 v5, v69
	v_mov_b32_e32 v6, v70
	v_mov_b32_e32 v7, v71
	s_branch .LBB0_84

; DI void transpose_job(const float* __restrict__ src, int K, int N, int Npad, bf16_t* __restrict__ dst, int mode, char* smem) {
;     ...
;   for (int tile = blockIdx.x; tile < tn * tk; tile += gridDim.x) {
;     const int n0 = (tile % tn) * 64, k0 = (tile / tn) * 64;
; #pragma unroll
;     for (int i = 0; i < 4; ++i) {
;       const int kr = (tid >> 4) + 16 * i, nc = (tid & 15) * 4, n = n0 + nc;
;       float4 v = make_float4(0.f, 0.f, 0.f, 0.f);
;       if (n < N) { const f32x4 t4 = __builtin_nontemporal_load((const f32x4*)(src + (size_t)(k0 + kr) * N + n)); v = make_float4(t4[0], t4[1], t4[2], t4[3]); }
;       t[kr * 65 + nc + 0] = v.x; t[kr * 65 + nc + 1] = v.y; t[kr * 65 + nc + 2] = v.z; t[kr * 65 + nc + 3] = v.w;
;     }
.LBB0_96:
	s_or_saveexec_b64 s[18:19], s[16:17]
	s_lshl_b32 s16, s28, 6
	v_mov_b32_e32 v4, 0
	v_mov_b32_e32 v5, 0
	v_mov_b32_e32 v6, 0
	v_mov_b32_e32 v7, 0
	v_mov_b32_e32 v0, 0
	v_mov_b32_e32 v1, 0
	v_mov_b32_e32 v2, 0
	v_mov_b32_e32 v3, 0
	s_xor_b64 exec, exec, s[18:19]
	s_cbranch_execz .LBB0_93
	v_ashrrev_i32_e32 v11, 31, v10
	v_lshl_add_u64 v[10:11], v[10:11], 2, s[14:15]
	v_add_u32_e32 v27, s16, v12
	v_mad_i64_i32 v[0:1], s[30:31], v27, s22, v[10:11]
	global_load_dwordx4 v[0:3], v[0:1], off nt
	v_add_u32_e32 v4, 16, v27
	v_mad_i64_i32 v[4:5], s[30:31], v4, s22, v[10:11]
	global_load_dwordx4 v[4:7], v[4:5], off nt
	v_add_u32_e32 v64, 32, v27
	v_add_u32_e32 v68, 48, v27
	v_mad_i64_i32 v[64:65], s[30:31], v64, s22, v[10:11]
	v_mad_i64_i32 v[68:69], s[30:31], v68, s22, v[10:11]
	global_load_dwordx4 v[64:67], v[64:65], off nt
	s_nop 0
	global_load_dwordx4 v[68:71], v[68:69], off nt
	s_waitcnt vmcnt(3)
	ds_write2_b32 v17, v0, v1 offset1:1
	ds_write2_b32 v17, v2, v3 offset0:2 offset1:3
	s_waitcnt vmcnt(2)
	ds_write2_b32 v18, v4, v5 offset1:1
	ds_write2_b32 v19, v6, v7 offset1:1
	s_waitcnt vmcnt(0)
	v_mov_b32_e32 v0, v64
	v_mov_b32_e32 v1, v65
	v_mov_b32_e32 v2, v66
	v_mov_b32_e32 v3, v67
	v_mov_b32_e32 v4, v68
	v_mov_b32_e32 v5, v69
	v_mov_b32_e32 v6, v70
	v_mov_b32_e32 v7, v71
	s_branch .LBB0_93

; DI void transpose_job(const float* __restrict__ src, int K, int N, int Npad, bf16_t* __restrict__ dst, int mode, char* smem) {
;     ...
;   for (int tile = blockIdx.x; tile < tn * tk; tile += gridDim.x) {
;     const int n0 = (tile % tn) * 64, k0 = (tile / tn) * 64;
; #pragma unroll
;     for (int i = 0; i < 4; ++i) {
;       const int kr = (tid >> 4) + 16 * i, nc = (tid & 15) * 4, n = n0 + nc;
;       float4 v = make_float4(0.f, 0.f, 0.f, 0.f);
;       if (n < N) { const f32x4 t4 = __builtin_nontemporal_load((const f32x4*)(src + (size_t)(k0 + kr) * N + n)); v = make_float4(t4[0], t4[1], t4[2], t4[3]); }
;       t[kr * 65 + nc + 0] = v.x; t[kr * 65 + nc + 1] = v.y; t[kr * 65 + nc + 2] = v.z; t[kr * 65 + nc + 3] = v.w;
;     }
.LBB0_110:
	s_or_saveexec_b64 s[14:15], s[2:3]
	s_lshl_b32 s2, s19, 6
	v_mov_b32_e32 v4, 0
	v_mov_b32_e32 v5, 0
	v_mov_b32_e32 v6, 0
	v_mov_b32_e32 v7, 0
	v_mov_b32_e32 v0, 0
	v_mov_b32_e32 v1, 0
	v_mov_b32_e32 v2, 0
	v_mov_b32_e32 v3, 0
	s_xor_b64 exec, exec, s[14:15]
	s_cbranch_execz .LBB0_107
	v_add_u32_e32 v28, s2, v14
	v_ashrrev_i32_e32 v13, 31, v12
	v_ashrrev_i32_e32 v29, 31, v28
	v_lshl_add_u64 v[12:13], v[12:13], 2, s[12:13]
	v_lshlrev_b64 v[0:1], 13, v[28:29]
	v_add_u32_e32 v4, 16, v28
	v_lshl_add_u64 v[0:1], v[12:13], 0, v[0:1]
	v_ashrrev_i32_e32 v5, 31, v4
	global_load_dwordx4 v[0:3], v[0:1], off nt
	v_lshlrev_b64 v[4:5], 13, v[4:5]
	v_lshl_add_u64 v[4:5], v[12:13], 0, v[4:5]
	global_load_dwordx4 v[4:7], v[4:5], off nt
	v_add_u32_e32 v64, 32, v28
	v_add_u32_e32 v68, 48, v28
	v_ashrrev_i32_e32 v65, 31, v64
	v_ashrrev_i32_e32 v69, 31, v68
	v_lshlrev_b64 v[64:65], 13, v[64:65]
	v_lshlrev_b64 v[68:69], 13, v[68:69]
	v_lshl_add_u64 v[64:65], v[12:13], 0, v[64:65]
	v_lshl_add_u64 v[68:69], v[12:13], 0, v[68:69]
	global_load_dwordx4 v[64:67], v[64:65], off nt
	s_nop 0
	global_load_dwordx4 v[68:71], v[68:69], off nt
	s_waitcnt vmcnt(3)
	ds_write2_b32 v18, v0, v1 offset1:1
	ds_write2_b32 v18, v2, v3 offset0:2 offset1:3
	s_waitcnt vmcnt(2)
	ds_write2_b32 v19, v4, v5 offset1:1
	ds_write2_b32 v20, v6, v7 offset1:1
	s_waitcnt vmcnt(0)
	v_mov_b32_e32 v0, v64
	v_mov_b32_e32 v1, v65
	v_mov_b32_e32 v2, v66
	v_mov_b32_e32 v3, v67
	v_mov_b32_e32 v4, v68
	v_mov_b32_e32 v5, v69
	v_mov_b32_e32 v6, v70
	v_mov_b32_e32 v7, v71
	s_branch .LBB0_107

; DI void transpose_job(const float* __restrict__ src, int K, int N, int Npad, bf16_t* __restrict__ dst, int mode, char* smem) {
;     ...
;   for (int tile = blockIdx.x; tile < tn * tk; tile += gridDim.x) {
;     const int n0 = (tile % tn) * 64, k0 = (tile / tn) * 64;
; #pragma unroll
;     for (int i = 0; i < 4; ++i) {
;       const int kr = (tid >> 4) + 16 * i, nc = (tid & 15) * 4, n = n0 + nc;
;       float4 v = make_float4(0.f, 0.f, 0.f, 0.f);
;       if (n < N) { const f32x4 t4 = __builtin_nontemporal_load((const f32x4*)(src + (size_t)(k0 + kr) * N + n)); v = make_float4(t4[0], t4[1], t4[2], t4[3]); }
;       t[kr * 65 + nc + 0] = v.x; t[kr * 65 + nc + 1] = v.y; t[kr * 65 + nc + 2] = v.z; t[kr * 65 + nc + 3] = v.w;
;     }
.LBB0_117:
	s_or_saveexec_b64 s[16:17], s[14:15]
	s_lshl_b32 s14, s26, 6
	v_mov_b32_e32 v4, 0
	v_mov_b32_e32 v5, 0
	v_mov_b32_e32 v6, 0
	v_mov_b32_e32 v7, 0
	v_mov_b32_e32 v0, 0
	v_mov_b32_e32 v1, 0
	v_mov_b32_e32 v2, 0
	v_mov_b32_e32 v3, 0
	s_xor_b64 exec, exec, s[16:17]
	s_cbranch_execz .LBB0_114
	v_add_u32_e32 v26, s14, v12
	v_ashrrev_i32_e32 v11, 31, v10
	v_ashrrev_i32_e32 v27, 31, v26
	v_lshl_add_u64 v[10:11], v[10:11], 2, s[2:3]
	v_lshlrev_b64 v[0:1], 13, v[26:27]
	v_add_u32_e32 v4, 16, v26
	v_lshl_add_u64 v[0:1], v[10:11], 0, v[0:1]
	v_ashrrev_i32_e32 v5, 31, v4
	global_load_dwordx4 v[0:3], v[0:1], off nt
	v_lshlrev_b64 v[4:5], 13, v[4:5]
	v_lshl_add_u64 v[4:5], v[10:11], 0, v[4:5]
	global_load_dwordx4 v[4:7], v[4:5], off nt
	v_add_u32_e32 v64, 32, v26
	v_add_u32_e32 v68, 48, v26
	v_ashrrev_i32_e32 v65, 31, v64
	v_ashrrev_i32_e32 v69, 31, v68
	v_lshlrev_b64 v[64:65], 13, v[64:65]
	v_lshlrev_b64 v[68:69], 13, v[68:69]
	v_lshl_add_u64 v[64:65], v[10:11], 0, v[64:65]
	v_lshl_add_u64 v[68:69], v[10:11], 0, v[68:69]
	global_load_dwordx4 v[64:67], v[64:65], off nt
	s_nop 0
	global_load_dwordx4 v[68:71], v[68:69], off nt
	s_waitcnt vmcnt(3)
	ds_write2_b32 v16, v0, v1 offset1:1
	ds_write2_b32 v16, v2, v3 offset0:2 offset1:3
	s_waitcnt vmcnt(2)
	ds_write2_b32 v17, v4, v5 offset1:1
	ds_write2_b32 v18, v6, v7 offset1:1
	s_waitcnt vmcnt(0)
	v_mov_b32_e32 v0, v64
	v_mov_b32_e32 v1, v65
	v_mov_b32_e32 v2, v66
	v_mov_b32_e32 v3, v67
	v_mov_b32_e32 v4, v68
	v_mov_b32_e32 v5, v69
	v_mov_b32_e32 v6, v70
	v_mov_b32_e32 v7, v71
	s_branch .LBB0_114

; DI void transpose_job(const float* __restrict__ src, int K, int N, int Npad, bf16_t* __restrict__ dst, int mode, char* smem) {
;     ...
;   for (int tile = blockIdx.x; tile < tn * tk; tile += gridDim.x) {
;     const int n0 = (tile % tn) * 64, k0 = (tile / tn) * 64;
; #pragma unroll
;     for (int i = 0; i < 4; ++i) {
;       const int kr = (tid >> 4) + 16 * i, nc = (tid & 15) * 4, n = n0 + nc;
;       float4 v = make_float4(0.f, 0.f, 0.f, 0.f);
;       if (n < N) { const f32x4 t4 = __builtin_nontemporal_load((const f32x4*)(src + (size_t)(k0 + kr) * N + n)); v = make_float4(t4[0], t4[1], t4[2], t4[3]); }
;       t[kr * 65 + nc + 0] = v.x; t[kr * 65 + nc + 1] = v.y; t[kr * 65 + nc + 2] = v.z; t[kr * 65 + nc + 3] = v.w;
;     }
.LBB0_124:
	s_or_saveexec_b64 s[16:17], s[14:15]
	s_lshl_b32 s14, s26, 6
	v_mov_b32_e32 v4, 0
	v_mov_b32_e32 v5, 0
	v_mov_b32_e32 v6, 0
	v_mov_b32_e32 v7, 0
	v_mov_b32_e32 v0, 0
	v_mov_b32_e32 v1, 0
	v_mov_b32_e32 v2, 0
	v_mov_b32_e32 v3, 0
	s_xor_b64 exec, exec, s[16:17]
	s_cbranch_execz .LBB0_121
	v_add_u32_e32 v20, s14, v12
	v_ashrrev_i32_e32 v11, 31, v10
	v_ashrrev_i32_e32 v21, 31, v20
	v_lshl_add_u64 v[10:11], v[10:11], 2, s[2:3]
	v_lshlrev_b64 v[0:1], 13, v[20:21]
	v_add_u32_e32 v4, 16, v20
	v_lshl_add_u64 v[0:1], v[10:11], 0, v[0:1]
	v_ashrrev_i32_e32 v5, 31, v4
	global_load_dwordx4 v[0:3], v[0:1], off nt
	v_lshlrev_b64 v[4:5], 13, v[4:5]
	v_lshl_add_u64 v[4:5], v[10:11], 0, v[4:5]
	global_load_dwordx4 v[4:7], v[4:5], off nt
	v_add_u32_e32 v64, 32, v20
	v_add_u32_e32 v68, 48, v20
	v_ashrrev_i32_e32 v65, 31, v64
	v_ashrrev_i32_e32 v69, 31, v68
	v_lshlrev_b64 v[64:65], 13, v[64:65]
	v_lshlrev_b64 v[68:69], 13, v[68:69]
	v_lshl_add_u64 v[64:65], v[10:11], 0, v[64:65]
	v_lshl_add_u64 v[68:69], v[10:11], 0, v[68:69]
	global_load_dwordx4 v[64:67], v[64:65], off nt
	s_nop 0
	global_load_dwordx4 v[68:71], v[68:69], off nt
	s_waitcnt vmcnt(3)
	ds_write2_b32 v16, v0, v1 offset1:1
	ds_write2_b32 v16, v2, v3 offset0:2 offset1:3
	s_waitcnt vmcnt(2)
	ds_write2_b32 v17, v4, v5 offset1:1
	ds_write2_b32 v18, v6, v7 offset1:1
	s_waitcnt vmcnt(0)
	v_mov_b32_e32 v0, v64
	v_mov_b32_e32 v1, v65
	v_mov_b32_e32 v2, v66
	v_mov_b32_e32 v3, v67
	v_mov_b32_e32 v4, v68
	v_mov_b32_e32 v5, v69
	v_mov_b32_e32 v6, v70
	v_mov_b32_e32 v7, v71
	s_branch .LBB0_121
